# P6 panel exchange: redundant mid s_barrier removed (row owners poll for themselves; waves 4-7 touch no LDS between the first and final barrier)
# baseline (speedup 1.0000x reference)
.LBB0_563:
	s_waitcnt lgkmcnt(0)
	s_and_b64 vcc, exec, s[2:3]
	s_cbranch_vccnz .LBB0_565
	v_lshlrev_b64 v[96:97], 5, v[96:97]
	v_lshl_add_u64 v[96:97], s[12:13], 0, v[96:97]
	s_mov_b32 s100, 0x400000
	s_sleep 16
